# Y-GEMM tanh-GELU epilogue regenerated with packed f32 VALU (same ops, two elements per instruction), on top of the f32-MFMA gate
# speedup vs baseline: 1.0064x; 1.0025x over previous
; #define LAS __attribute__((address_space(3)))
; __device__ __forceinline__ unsigned cvt_pk_bf16(float lo, float hi) { const f32x2 v = {lo, hi}; const bf16x2_t b = __builtin_convertvector(v, bf16x2_t); return __builtin_bit_cast(unsigned, b); }
; __device__ __forceinline__ void store16_wt(void* p, u32x4 v) { asm volatile("global_store_dwordx4 %0, %1, off sc1\n\ts_nop 1" :: "v"(p), "v"(v) : "memory"); }
; __device__ __forceinline__ u32x4 ror8_u4(u32x4 v) { const unsigned a = ror8_u(v.x), b = ror8_u(v.y), c = ror8_u(v.z), d = ror8_u(v.w); return (u32x4){a, b, c, d}; }
; __device__ __forceinline__ float fast_gelu_tanh(float x) { const float p = __builtin_fmaf(x * x, -0.10294324f, -2.3022082f);
;     return x * __builtin_amdgcn_rcpf(1.f + __builtin_amdgcn_exp2f(p * x)); }
;     __device__ __forceinline__ void epi(AccT& acc, const Unit& u, LAS unsigned char* lds, int wr, int wc, int fr, int fq) const {
; #pragma unroll
;         for (int ai = 0; ai < 2; ++ai)
; #pragma unroll
;             for (int m = 0; m < 4; ++m) { const bool lo = fr < 8; const int row = u.pm * 256 + ai * 128 + wr * 64 + m * 16 + (fr & 7); bf16_t* rp = ZT + (size_t)u.pn * T * 16 + (size_t)row * 256 + wc * 64 + (lo ? 0 : 32) + 8 * fq; u32x4 w[2];
; #pragma unroll
;                 for (int bj = 0; bj < 2; ++bj) { const f32x4 v0 = acc[ai][bj][m][0], v1 = acc[ai][bj][m][1];
;                     w[bj].x = cvt_pk_bf16(fast_gelu_tanh(v0[0]), fast_gelu_tanh(v0[1])); w[bj].y = cvt_pk_bf16(fast_gelu_tanh(v0[2]), fast_gelu_tanh(v0[3]));
;                     w[bj].z = cvt_pk_bf16(fast_gelu_tanh(v1[0]), fast_gelu_tanh(v1[1])); w[bj].w = cvt_pk_bf16(fast_gelu_tanh(v1[2]), fast_gelu_tanh(v1[3])); }
;                 const u32x4 r0 = ror8_u4(w[0]), r1 = ror8_u4(w[1]); store16_wt(rp, lo ? w[0] : r1); store16_wt(rp + 8 * 256, lo ? r0 : w[1]); }
;     }
.LBB0_360:
	v_and_or_b32 v146, v132, 7, s22
	v_add_u32_e32 v146, s0, v146
	v_cmp_gt_u32_e32 vcc, 8, v133
	s_lshl_b64 s[4:5], s[12:13], 19
	s_add_u32 s0, s34, s4
	s_addc_u32 s5, s35, s5
	s_add_u32 s4, s0, 0x9000000
	s_addc_u32 s5, s5, 0
	s_mov_b32 s1, 0
	s_lshl_b32 s0, s17, 7
	s_mov_b64 s[6:7], 0x1000
	v_mov_b32_e32 v140, 0xbdd2d3e8
	v_mov_b32_e32 v141, 0xbdd2d3e8
	v_mov_b32_e32 v142, 0xc0135761
	v_mov_b32_e32 v143, 0xc0135761
	v_mov_b32_e32 v144, 1.0
	v_mov_b32_e32 v145, 1.0
	v_cndmask_b32_e64 v150, 64, 0, vcc
	v_and_b32_e32 v151, 0x70, v132
	v_add_u32_e32 v150, v150, v151
	v_mov_b32_e32 v151, 0
	v_lshl_add_u64 v[148:149], s[4:5], 0, v[150:151]
	v_lshl_add_u64 v[148:149], v[148:149], 0, s[0:1]
	v_pk_mul_f32 v[160:161], v[124:125], v[124:125]
	v_pk_mul_f32 v[162:163], v[126:127], v[126:127]
	v_pk_mul_f32 v[164:165], v[120:121], v[120:121]
	v_pk_mul_f32 v[166:167], v[122:123], v[122:123]
	v_pk_mul_f32 v[168:169], v[116:117], v[116:117]
	v_pk_mul_f32 v[170:171], v[118:119], v[118:119]
	v_pk_mul_f32 v[172:173], v[112:113], v[112:113]
	v_pk_mul_f32 v[174:175], v[114:115], v[114:115]
	v_pk_fma_f32 v[160:161], v[160:161], v[140:141], v[142:143]
	v_pk_fma_f32 v[162:163], v[162:163], v[140:141], v[142:143]
	v_pk_fma_f32 v[164:165], v[164:165], v[140:141], v[142:143]
	v_pk_fma_f32 v[166:167], v[166:167], v[140:141], v[142:143]
	v_pk_fma_f32 v[168:169], v[168:169], v[140:141], v[142:143]
	v_pk_fma_f32 v[170:171], v[170:171], v[140:141], v[142:143]
	v_pk_fma_f32 v[172:173], v[172:173], v[140:141], v[142:143]
	v_pk_fma_f32 v[174:175], v[174:175], v[140:141], v[142:143]
	v_pk_mul_f32 v[160:161], v[124:125], v[160:161]
	v_pk_mul_f32 v[162:163], v[126:127], v[162:163]
	v_pk_mul_f32 v[164:165], v[120:121], v[164:165]
	v_pk_mul_f32 v[166:167], v[122:123], v[166:167]
	v_pk_mul_f32 v[168:169], v[116:117], v[168:169]
	v_pk_mul_f32 v[170:171], v[118:119], v[170:171]
	v_pk_mul_f32 v[172:173], v[112:113], v[172:173]
	v_pk_mul_f32 v[174:175], v[114:115], v[174:175]
	v_exp_f32_e32 v160, v160
	v_exp_f32_e32 v161, v161
	v_exp_f32_e32 v162, v162
	v_exp_f32_e32 v163, v163
	v_exp_f32_e32 v164, v164
	v_exp_f32_e32 v165, v165
	v_exp_f32_e32 v166, v166
	v_exp_f32_e32 v167, v167
	v_exp_f32_e32 v168, v168
	v_exp_f32_e32 v169, v169
	v_exp_f32_e32 v170, v170
	v_exp_f32_e32 v171, v171
	v_exp_f32_e32 v172, v172
	v_exp_f32_e32 v173, v173
	v_exp_f32_e32 v174, v174
	v_exp_f32_e32 v175, v175
	v_add_u32_e32 v152, 0, v146
	v_mov_b32_e32 v153, 0
	v_pk_add_f32 v[160:161], v[160:161], v[144:145]
	v_pk_add_f32 v[162:163], v[162:163], v[144:145]
	v_pk_add_f32 v[164:165], v[164:165], v[144:145]
	v_pk_add_f32 v[166:167], v[166:167], v[144:145]
	v_pk_add_f32 v[168:169], v[168:169], v[144:145]
	v_pk_add_f32 v[170:171], v[170:171], v[144:145]
	v_pk_add_f32 v[172:173], v[172:173], v[144:145]
	v_pk_add_f32 v[174:175], v[174:175], v[144:145]
	v_rcp_f32_e32 v160, v160
	v_rcp_f32_e32 v161, v161
	v_rcp_f32_e32 v162, v162
	v_rcp_f32_e32 v163, v163
	v_rcp_f32_e32 v164, v164
	v_rcp_f32_e32 v165, v165
	v_rcp_f32_e32 v166, v166
	v_rcp_f32_e32 v167, v167
	v_rcp_f32_e32 v168, v168
	v_rcp_f32_e32 v169, v169
	v_rcp_f32_e32 v170, v170
	v_rcp_f32_e32 v171, v171
	v_rcp_f32_e32 v172, v172
	v_rcp_f32_e32 v173, v173
	v_rcp_f32_e32 v174, v174
	v_rcp_f32_e32 v175, v175
	v_lshlrev_b64 v[152:153], 9, v[152:153]
	v_lshl_add_u64 v[152:153], v[148:149], 0, v[152:153]
	v_pk_mul_f32 v[124:125], v[124:125], v[160:161]
	v_pk_mul_f32 v[126:127], v[126:127], v[162:163]
	v_pk_mul_f32 v[120:121], v[120:121], v[164:165]
	v_pk_mul_f32 v[122:123], v[122:123], v[166:167]
	v_pk_mul_f32 v[116:117], v[116:117], v[168:169]
	v_pk_mul_f32 v[118:119], v[118:119], v[170:171]
	v_pk_mul_f32 v[112:113], v[112:113], v[172:173]
	v_pk_mul_f32 v[114:115], v[114:115], v[174:175]
	v_cvt_pk_bf16_f32 v180, v124, v125
	v_cvt_pk_bf16_f32 v181, v126, v127
	v_cvt_pk_bf16_f32 v182, v120, v121
	v_cvt_pk_bf16_f32 v183, v122, v123
	v_cvt_pk_bf16_f32 v184, v116, v117
	v_cvt_pk_bf16_f32 v185, v118, v119
	v_cvt_pk_bf16_f32 v186, v112, v113
	v_cvt_pk_bf16_f32 v187, v114, v115
	v_mov_b32_dpp v190, v184 row_ror:8 row_mask:0xf bank_mask:0xf bound_ctrl:1
	v_mov_b32_dpp v191, v185 row_ror:8 row_mask:0xf bank_mask:0xf bound_ctrl:1
	v_mov_b32_dpp v192, v186 row_ror:8 row_mask:0xf bank_mask:0xf bound_ctrl:1
	v_mov_b32_dpp v193, v187 row_ror:8 row_mask:0xf bank_mask:0xf bound_ctrl:1
	v_cndmask_b32_e32 v194, v190, v180, vcc
	v_cndmask_b32_e32 v195, v191, v181, vcc
	v_cndmask_b32_e32 v196, v192, v182, vcc
	v_cndmask_b32_e32 v197, v193, v183, vcc
	global_store_dwordx4 v[152:153], v[194:197], off sc1
	s_nop 1
	v_mov_b32_dpp v190, v180 row_ror:8 row_mask:0xf bank_mask:0xf bound_ctrl:1
	v_mov_b32_dpp v191, v181 row_ror:8 row_mask:0xf bank_mask:0xf bound_ctrl:1
	v_mov_b32_dpp v192, v182 row_ror:8 row_mask:0xf bank_mask:0xf bound_ctrl:1
	v_mov_b32_dpp v193, v183 row_ror:8 row_mask:0xf bank_mask:0xf bound_ctrl:1
	v_cndmask_b32_e32 v198, v184, v190, vcc
	v_cndmask_b32_e32 v199, v185, v191, vcc
	v_cndmask_b32_e32 v200, v186, v192, vcc
	v_cndmask_b32_e32 v201, v187, v193, vcc
	v_lshl_add_u64 v[152:153], v[152:153], 0, s[6:7]
	global_store_dwordx4 v[152:153], v[198:201], off sc1
	s_nop 1
	v_pk_mul_f32 v[160:161], v[108:109], v[108:109]
	v_pk_mul_f32 v[162:163], v[110:111], v[110:111]
	v_pk_mul_f32 v[164:165], v[104:105], v[104:105]
	v_pk_mul_f32 v[166:167], v[106:107], v[106:107]
	v_pk_mul_f32 v[168:169], v[100:101], v[100:101]
	v_pk_mul_f32 v[170:171], v[102:103], v[102:103]
	v_pk_mul_f32 v[172:173], v[96:97], v[96:97]
	v_pk_mul_f32 v[174:175], v[98:99], v[98:99]
	v_pk_fma_f32 v[160:161], v[160:161], v[140:141], v[142:143]
	v_pk_fma_f32 v[162:163], v[162:163], v[140:141], v[142:143]
; #define LAS __attribute__((address_space(3)))
; __device__ __forceinline__ unsigned cvt_pk_bf16(float lo, float hi) { const f32x2 v = {lo, hi}; const bf16x2_t b = __builtin_convertvector(v, bf16x2_t); return __builtin_bit_cast(unsigned, b); }
; __device__ __forceinline__ void store16_wt(void* p, u32x4 v) { asm volatile("global_store_dwordx4 %0, %1, off sc1\n\ts_nop 1" :: "v"(p), "v"(v) : "memory"); }
; __device__ __forceinline__ u32x4 ror8_u4(u32x4 v) { const unsigned a = ror8_u(v.x), b = ror8_u(v.y), c = ror8_u(v.z), d = ror8_u(v.w); return (u32x4){a, b, c, d}; }
; __device__ __forceinline__ float fast_gelu_tanh(float x) { const float p = __builtin_fmaf(x * x, -0.10294324f, -2.3022082f);
;     return x * __builtin_amdgcn_rcpf(1.f + __builtin_amdgcn_exp2f(p * x)); }
;     __device__ __forceinline__ void epi(AccT& acc, const Unit& u, LAS unsigned char* lds, int wr, int wc, int fr, int fq) const {
; #pragma unroll
;         for (int ai = 0; ai < 2; ++ai)
; #pragma unroll
;             for (int m = 0; m < 4; ++m) { const bool lo = fr < 8; const int row = u.pm * 256 + ai * 128 + wr * 64 + m * 16 + (fr & 7); bf16_t* rp = ZT + (size_t)u.pn * T * 16 + (size_t)row * 256 + wc * 64 + (lo ? 0 : 32) + 8 * fq; u32x4 w[2];
; #pragma unroll
;                 for (int bj = 0; bj < 2; ++bj) { const f32x4 v0 = acc[ai][bj][m][0], v1 = acc[ai][bj][m][1];
;                     w[bj].x = cvt_pk_bf16(fast_gelu_tanh(v0[0]), fast_gelu_tanh(v0[1])); w[bj].y = cvt_pk_bf16(fast_gelu_tanh(v0[2]), fast_gelu_tanh(v0[3]));
;                     w[bj].z = cvt_pk_bf16(fast_gelu_tanh(v1[0]), fast_gelu_tanh(v1[1])); w[bj].w = cvt_pk_bf16(fast_gelu_tanh(v1[2]), fast_gelu_tanh(v1[3])); }
;                 const u32x4 r0 = ror8_u4(w[0]), r1 = ror8_u4(w[1]); store16_wt(rp, lo ? w[0] : r1); store16_wt(rp + 8 * 256, lo ? r0 : w[1]); }
;     }
	v_pk_fma_f32 v[164:165], v[164:165], v[140:141], v[142:143]
	v_pk_fma_f32 v[166:167], v[166:167], v[140:141], v[142:143]
	v_pk_fma_f32 v[168:169], v[168:169], v[140:141], v[142:143]
	v_pk_fma_f32 v[170:171], v[170:171], v[140:141], v[142:143]
	v_pk_fma_f32 v[172:173], v[172:173], v[140:141], v[142:143]
	v_pk_fma_f32 v[174:175], v[174:175], v[140:141], v[142:143]
	v_pk_mul_f32 v[160:161], v[108:109], v[160:161]
	v_pk_mul_f32 v[162:163], v[110:111], v[162:163]
	v_pk_mul_f32 v[164:165], v[104:105], v[164:165]
	v_pk_mul_f32 v[166:167], v[106:107], v[166:167]
	v_pk_mul_f32 v[168:169], v[100:101], v[168:169]
	v_pk_mul_f32 v[170:171], v[102:103], v[170:171]
	v_pk_mul_f32 v[172:173], v[96:97], v[172:173]
	v_pk_mul_f32 v[174:175], v[98:99], v[174:175]
	v_exp_f32_e32 v160, v160
	v_exp_f32_e32 v161, v161
	v_exp_f32_e32 v162, v162
	v_exp_f32_e32 v163, v163
	v_exp_f32_e32 v164, v164
	v_exp_f32_e32 v165, v165
	v_exp_f32_e32 v166, v166
	v_exp_f32_e32 v167, v167
	v_exp_f32_e32 v168, v168
	v_exp_f32_e32 v169, v169
	v_exp_f32_e32 v170, v170
	v_exp_f32_e32 v171, v171
	v_exp_f32_e32 v172, v172
	v_exp_f32_e32 v173, v173
	v_exp_f32_e32 v174, v174
	v_exp_f32_e32 v175, v175
	v_add_u32_e32 v152, 16, v146
	v_mov_b32_e32 v153, 0
	v_pk_add_f32 v[160:161], v[160:161], v[144:145]
	v_pk_add_f32 v[162:163], v[162:163], v[144:145]
	v_pk_add_f32 v[164:165], v[164:165], v[144:145]
	v_pk_add_f32 v[166:167], v[166:167], v[144:145]
	v_pk_add_f32 v[168:169], v[168:169], v[144:145]
	v_pk_add_f32 v[170:171], v[170:171], v[144:145]
	v_pk_add_f32 v[172:173], v[172:173], v[144:145]
	v_pk_add_f32 v[174:175], v[174:175], v[144:145]
	v_rcp_f32_e32 v160, v160
	v_rcp_f32_e32 v161, v161
	v_rcp_f32_e32 v162, v162
	v_rcp_f32_e32 v163, v163
	v_rcp_f32_e32 v164, v164
	v_rcp_f32_e32 v165, v165
	v_rcp_f32_e32 v166, v166
	v_rcp_f32_e32 v167, v167
	v_rcp_f32_e32 v168, v168
	v_rcp_f32_e32 v169, v169
	v_rcp_f32_e32 v170, v170
	v_rcp_f32_e32 v171, v171
	v_rcp_f32_e32 v172, v172
	v_rcp_f32_e32 v173, v173
	v_rcp_f32_e32 v174, v174
	v_rcp_f32_e32 v175, v175
	v_lshlrev_b64 v[152:153], 9, v[152:153]
	v_lshl_add_u64 v[152:153], v[148:149], 0, v[152:153]
	v_pk_mul_f32 v[108:109], v[108:109], v[160:161]
	v_pk_mul_f32 v[110:111], v[110:111], v[162:163]
	v_pk_mul_f32 v[104:105], v[104:105], v[164:165]
	v_pk_mul_f32 v[106:107], v[106:107], v[166:167]
	v_pk_mul_f32 v[100:101], v[100:101], v[168:169]
	v_pk_mul_f32 v[102:103], v[102:103], v[170:171]
	v_pk_mul_f32 v[96:97], v[96:97], v[172:173]
	v_pk_mul_f32 v[98:99], v[98:99], v[174:175]
	v_cvt_pk_bf16_f32 v180, v108, v109
	v_cvt_pk_bf16_f32 v181, v110, v111
	v_cvt_pk_bf16_f32 v182, v104, v105
	v_cvt_pk_bf16_f32 v183, v106, v107
	v_cvt_pk_bf16_f32 v184, v100, v101
	v_cvt_pk_bf16_f32 v185, v102, v103
	v_cvt_pk_bf16_f32 v186, v96, v97
	v_cvt_pk_bf16_f32 v187, v98, v99
	v_mov_b32_dpp v190, v184 row_ror:8 row_mask:0xf bank_mask:0xf bound_ctrl:1
	v_mov_b32_dpp v191, v185 row_ror:8 row_mask:0xf bank_mask:0xf bound_ctrl:1
	v_mov_b32_dpp v192, v186 row_ror:8 row_mask:0xf bank_mask:0xf bound_ctrl:1
	v_mov_b32_dpp v193, v187 row_ror:8 row_mask:0xf bank_mask:0xf bound_ctrl:1
	v_cndmask_b32_e32 v194, v190, v180, vcc
	v_cndmask_b32_e32 v195, v191, v181, vcc
	v_cndmask_b32_e32 v196, v192, v182, vcc
	v_cndmask_b32_e32 v197, v193, v183, vcc
	global_store_dwordx4 v[152:153], v[194:197], off sc1
	s_nop 1
	v_mov_b32_dpp v190, v180 row_ror:8 row_mask:0xf bank_mask:0xf bound_ctrl:1
	v_mov_b32_dpp v191, v181 row_ror:8 row_mask:0xf bank_mask:0xf bound_ctrl:1
	v_mov_b32_dpp v192, v182 row_ror:8 row_mask:0xf bank_mask:0xf bound_ctrl:1
	v_mov_b32_dpp v193, v183 row_ror:8 row_mask:0xf bank_mask:0xf bound_ctrl:1
	v_cndmask_b32_e32 v198, v184, v190, vcc
	v_cndmask_b32_e32 v199, v185, v191, vcc
	v_cndmask_b32_e32 v200, v186, v192, vcc
	v_cndmask_b32_e32 v201, v187, v193, vcc
	v_lshl_add_u64 v[152:153], v[152:153], 0, s[6:7]
	global_store_dwordx4 v[152:153], v[198:201], off sc1
	s_nop 1
	v_pk_mul_f32 v[160:161], v[92:93], v[92:93]
	v_pk_mul_f32 v[162:163], v[94:95], v[94:95]
	v_pk_mul_f32 v[164:165], v[88:89], v[88:89]
	v_pk_mul_f32 v[166:167], v[90:91], v[90:91]
	v_pk_mul_f32 v[168:169], v[84:85], v[84:85]
	v_pk_mul_f32 v[170:171], v[86:87], v[86:87]
	v_pk_mul_f32 v[172:173], v[80:81], v[80:81]
	v_pk_mul_f32 v[174:175], v[82:83], v[82:83]
	v_pk_fma_f32 v[160:161], v[160:161], v[140:141], v[142:143]
	v_pk_fma_f32 v[162:163], v[162:163], v[140:141], v[142:143]
	v_pk_fma_f32 v[164:165], v[164:165], v[140:141], v[142:143]
	v_pk_fma_f32 v[166:167], v[166:167], v[140:141], v[142:143]
	v_pk_fma_f32 v[168:169], v[168:169], v[140:141], v[142:143]
	v_pk_fma_f32 v[170:171], v[170:171], v[140:141], v[142:143]
	v_pk_fma_f32 v[172:173], v[172:173], v[140:141], v[142:143]
	v_pk_fma_f32 v[174:175], v[174:175], v[140:141], v[142:143]
	v_pk_mul_f32 v[160:161], v[92:93], v[160:161]
	v_pk_mul_f32 v[162:163], v[94:95], v[162:163]
	v_pk_mul_f32 v[164:165], v[88:89], v[164:165]
	v_pk_mul_f32 v[166:167], v[90:91], v[166:167]
	v_pk_mul_f32 v[168:169], v[84:85], v[168:169]
	v_pk_mul_f32 v[170:171], v[86:87], v[170:171]
	v_pk_mul_f32 v[172:173], v[80:81], v[172:173]
	v_pk_mul_f32 v[174:175], v[82:83], v[174:175]
	v_exp_f32_e32 v160, v160
	v_exp_f32_e32 v161, v161
	v_exp_f32_e32 v162, v162
	v_exp_f32_e32 v163, v163
	v_exp_f32_e32 v164, v164
	v_exp_f32_e32 v165, v165
	v_exp_f32_e32 v166, v166
	v_exp_f32_e32 v167, v167
	v_exp_f32_e32 v168, v168
	v_exp_f32_e32 v169, v169
	v_exp_f32_e32 v170, v170
	v_exp_f32_e32 v171, v171
	v_exp_f32_e32 v172, v172
	v_exp_f32_e32 v173, v173
	v_exp_f32_e32 v174, v174
	v_exp_f32_e32 v175, v175
	v_add_u32_e32 v152, 32, v146
	v_mov_b32_e32 v153, 0
	v_pk_add_f32 v[160:161], v[160:161], v[144:145]
; #define LAS __attribute__((address_space(3)))
; __device__ __forceinline__ unsigned cvt_pk_bf16(float lo, float hi) { const f32x2 v = {lo, hi}; const bf16x2_t b = __builtin_convertvector(v, bf16x2_t); return __builtin_bit_cast(unsigned, b); }
; __device__ __forceinline__ void store16_wt(void* p, u32x4 v) { asm volatile("global_store_dwordx4 %0, %1, off sc1\n\ts_nop 1" :: "v"(p), "v"(v) : "memory"); }
; __device__ __forceinline__ u32x4 ror8_u4(u32x4 v) { const unsigned a = ror8_u(v.x), b = ror8_u(v.y), c = ror8_u(v.z), d = ror8_u(v.w); return (u32x4){a, b, c, d}; }
; __device__ __forceinline__ float fast_gelu_tanh(float x) { const float p = __builtin_fmaf(x * x, -0.10294324f, -2.3022082f);
;     return x * __builtin_amdgcn_rcpf(1.f + __builtin_amdgcn_exp2f(p * x)); }
;     __device__ __forceinline__ void epi(AccT& acc, const Unit& u, LAS unsigned char* lds, int wr, int wc, int fr, int fq) const {
; #pragma unroll
;         for (int ai = 0; ai < 2; ++ai)
; #pragma unroll
;             for (int m = 0; m < 4; ++m) { const bool lo = fr < 8; const int row = u.pm * 256 + ai * 128 + wr * 64 + m * 16 + (fr & 7); bf16_t* rp = ZT + (size_t)u.pn * T * 16 + (size_t)row * 256 + wc * 64 + (lo ? 0 : 32) + 8 * fq; u32x4 w[2];
; #pragma unroll
;                 for (int bj = 0; bj < 2; ++bj) { const f32x4 v0 = acc[ai][bj][m][0], v1 = acc[ai][bj][m][1];
;                     w[bj].x = cvt_pk_bf16(fast_gelu_tanh(v0[0]), fast_gelu_tanh(v0[1])); w[bj].y = cvt_pk_bf16(fast_gelu_tanh(v0[2]), fast_gelu_tanh(v0[3]));
;                     w[bj].z = cvt_pk_bf16(fast_gelu_tanh(v1[0]), fast_gelu_tanh(v1[1])); w[bj].w = cvt_pk_bf16(fast_gelu_tanh(v1[2]), fast_gelu_tanh(v1[3])); }
;                 const u32x4 r0 = ror8_u4(w[0]), r1 = ror8_u4(w[1]); store16_wt(rp, lo ? w[0] : r1); store16_wt(rp + 8 * 256, lo ? r0 : w[1]); }
;     }
	v_pk_add_f32 v[162:163], v[162:163], v[144:145]
	v_pk_add_f32 v[164:165], v[164:165], v[144:145]
	v_pk_add_f32 v[166:167], v[166:167], v[144:145]
	v_pk_add_f32 v[168:169], v[168:169], v[144:145]
	v_pk_add_f32 v[170:171], v[170:171], v[144:145]
	v_pk_add_f32 v[172:173], v[172:173], v[144:145]
	v_pk_add_f32 v[174:175], v[174:175], v[144:145]
	v_rcp_f32_e32 v160, v160
	v_rcp_f32_e32 v161, v161
	v_rcp_f32_e32 v162, v162
	v_rcp_f32_e32 v163, v163
	v_rcp_f32_e32 v164, v164
	v_rcp_f32_e32 v165, v165
	v_rcp_f32_e32 v166, v166
	v_rcp_f32_e32 v167, v167
	v_rcp_f32_e32 v168, v168
	v_rcp_f32_e32 v169, v169
	v_rcp_f32_e32 v170, v170
	v_rcp_f32_e32 v171, v171
	v_rcp_f32_e32 v172, v172
	v_rcp_f32_e32 v173, v173
	v_rcp_f32_e32 v174, v174
	v_rcp_f32_e32 v175, v175
	v_lshlrev_b64 v[152:153], 9, v[152:153]
	v_lshl_add_u64 v[152:153], v[148:149], 0, v[152:153]
	v_pk_mul_f32 v[92:93], v[92:93], v[160:161]
	v_pk_mul_f32 v[94:95], v[94:95], v[162:163]
	v_pk_mul_f32 v[88:89], v[88:89], v[164:165]
	v_pk_mul_f32 v[90:91], v[90:91], v[166:167]
	v_pk_mul_f32 v[84:85], v[84:85], v[168:169]
	v_pk_mul_f32 v[86:87], v[86:87], v[170:171]
	v_pk_mul_f32 v[80:81], v[80:81], v[172:173]
	v_pk_mul_f32 v[82:83], v[82:83], v[174:175]
	v_cvt_pk_bf16_f32 v180, v92, v93
	v_cvt_pk_bf16_f32 v181, v94, v95
	v_cvt_pk_bf16_f32 v182, v88, v89
	v_cvt_pk_bf16_f32 v183, v90, v91
	v_cvt_pk_bf16_f32 v184, v84, v85
	v_cvt_pk_bf16_f32 v185, v86, v87
	v_cvt_pk_bf16_f32 v186, v80, v81
	v_cvt_pk_bf16_f32 v187, v82, v83
	v_mov_b32_dpp v190, v184 row_ror:8 row_mask:0xf bank_mask:0xf bound_ctrl:1
	v_mov_b32_dpp v191, v185 row_ror:8 row_mask:0xf bank_mask:0xf bound_ctrl:1
	v_mov_b32_dpp v192, v186 row_ror:8 row_mask:0xf bank_mask:0xf bound_ctrl:1
	v_mov_b32_dpp v193, v187 row_ror:8 row_mask:0xf bank_mask:0xf bound_ctrl:1
	v_cndmask_b32_e32 v194, v190, v180, vcc
	v_cndmask_b32_e32 v195, v191, v181, vcc
	v_cndmask_b32_e32 v196, v192, v182, vcc
	v_cndmask_b32_e32 v197, v193, v183, vcc
	global_store_dwordx4 v[152:153], v[194:197], off sc1
	s_nop 1
	v_mov_b32_dpp v190, v180 row_ror:8 row_mask:0xf bank_mask:0xf bound_ctrl:1
	v_mov_b32_dpp v191, v181 row_ror:8 row_mask:0xf bank_mask:0xf bound_ctrl:1
	v_mov_b32_dpp v192, v182 row_ror:8 row_mask:0xf bank_mask:0xf bound_ctrl:1
	v_mov_b32_dpp v193, v183 row_ror:8 row_mask:0xf bank_mask:0xf bound_ctrl:1
	v_cndmask_b32_e32 v198, v184, v190, vcc
	v_cndmask_b32_e32 v199, v185, v191, vcc
	v_cndmask_b32_e32 v200, v186, v192, vcc
	v_cndmask_b32_e32 v201, v187, v193, vcc
	v_lshl_add_u64 v[152:153], v[152:153], 0, s[6:7]
	global_store_dwordx4 v[152:153], v[198:201], off sc1
	s_nop 1
	v_pk_mul_f32 v[160:161], v[76:77], v[76:77]
	v_pk_mul_f32 v[162:163], v[78:79], v[78:79]
	v_pk_mul_f32 v[164:165], v[72:73], v[72:73]
	v_pk_mul_f32 v[166:167], v[74:75], v[74:75]
	v_pk_mul_f32 v[168:169], v[68:69], v[68:69]
	v_pk_mul_f32 v[170:171], v[70:71], v[70:71]
	v_pk_mul_f32 v[172:173], v[64:65], v[64:65]
	v_pk_mul_f32 v[174:175], v[66:67], v[66:67]
	v_pk_fma_f32 v[160:161], v[160:161], v[140:141], v[142:143]
	v_pk_fma_f32 v[162:163], v[162:163], v[140:141], v[142:143]
	v_pk_fma_f32 v[164:165], v[164:165], v[140:141], v[142:143]
	v_pk_fma_f32 v[166:167], v[166:167], v[140:141], v[142:143]
	v_pk_fma_f32 v[168:169], v[168:169], v[140:141], v[142:143]
	v_pk_fma_f32 v[170:171], v[170:171], v[140:141], v[142:143]
	v_pk_fma_f32 v[172:173], v[172:173], v[140:141], v[142:143]
	v_pk_fma_f32 v[174:175], v[174:175], v[140:141], v[142:143]
	v_pk_mul_f32 v[160:161], v[76:77], v[160:161]
	v_pk_mul_f32 v[162:163], v[78:79], v[162:163]
	v_pk_mul_f32 v[164:165], v[72:73], v[164:165]
	v_pk_mul_f32 v[166:167], v[74:75], v[166:167]
	v_pk_mul_f32 v[168:169], v[68:69], v[168:169]
	v_pk_mul_f32 v[170:171], v[70:71], v[170:171]
	v_pk_mul_f32 v[172:173], v[64:65], v[172:173]
	v_pk_mul_f32 v[174:175], v[66:67], v[174:175]
	v_exp_f32_e32 v160, v160
	v_exp_f32_e32 v161, v161
	v_exp_f32_e32 v162, v162
	v_exp_f32_e32 v163, v163
	v_exp_f32_e32 v164, v164
	v_exp_f32_e32 v165, v165
	v_exp_f32_e32 v166, v166
	v_exp_f32_e32 v167, v167
	v_exp_f32_e32 v168, v168
	v_exp_f32_e32 v169, v169
	v_exp_f32_e32 v170, v170
	v_exp_f32_e32 v171, v171
	v_exp_f32_e32 v172, v172
	v_exp_f32_e32 v173, v173
	v_exp_f32_e32 v174, v174
	v_exp_f32_e32 v175, v175
	v_add_u32_e32 v152, 48, v146
	v_mov_b32_e32 v153, 0
	v_pk_add_f32 v[160:161], v[160:161], v[144:145]
	v_pk_add_f32 v[162:163], v[162:163], v[144:145]
	v_pk_add_f32 v[164:165], v[164:165], v[144:145]
	v_pk_add_f32 v[166:167], v[166:167], v[144:145]
	v_pk_add_f32 v[168:169], v[168:169], v[144:145]
	v_pk_add_f32 v[170:171], v[170:171], v[144:145]
	v_pk_add_f32 v[172:173], v[172:173], v[144:145]
	v_pk_add_f32 v[174:175], v[174:175], v[144:145]
	v_rcp_f32_e32 v160, v160
	v_rcp_f32_e32 v161, v161
	v_rcp_f32_e32 v162, v162
	v_rcp_f32_e32 v163, v163
	v_rcp_f32_e32 v164, v164
	v_rcp_f32_e32 v165, v165
	v_rcp_f32_e32 v166, v166
	v_rcp_f32_e32 v167, v167
	v_rcp_f32_e32 v168, v168
	v_rcp_f32_e32 v169, v169
	v_rcp_f32_e32 v170, v170
	v_rcp_f32_e32 v171, v171
	v_rcp_f32_e32 v172, v172
	v_rcp_f32_e32 v173, v173
	v_rcp_f32_e32 v174, v174
	v_rcp_f32_e32 v175, v175
	v_lshlrev_b64 v[152:153], 9, v[152:153]
	v_lshl_add_u64 v[152:153], v[148:149], 0, v[152:153]
	v_pk_mul_f32 v[76:77], v[76:77], v[160:161]
	v_pk_mul_f32 v[78:79], v[78:79], v[162:163]
	v_pk_mul_f32 v[72:73], v[72:73], v[164:165]
	v_pk_mul_f32 v[74:75], v[74:75], v[166:167]
	v_pk_mul_f32 v[68:69], v[68:69], v[168:169]
	v_pk_mul_f32 v[70:71], v[70:71], v[170:171]
	v_pk_mul_f32 v[64:65], v[64:65], v[172:173]
	v_pk_mul_f32 v[66:67], v[66:67], v[174:175]
	v_cvt_pk_bf16_f32 v180, v76, v77
	v_cvt_pk_bf16_f32 v181, v78, v79
	v_cvt_pk_bf16_f32 v182, v72, v73
; #define LAS __attribute__((address_space(3)))
; __device__ __forceinline__ unsigned cvt_pk_bf16(float lo, float hi) { const f32x2 v = {lo, hi}; const bf16x2_t b = __builtin_convertvector(v, bf16x2_t); return __builtin_bit_cast(unsigned, b); }
; __device__ __forceinline__ void store16_wt(void* p, u32x4 v) { asm volatile("global_store_dwordx4 %0, %1, off sc1\n\ts_nop 1" :: "v"(p), "v"(v) : "memory"); }
; __device__ __forceinline__ u32x4 ror8_u4(u32x4 v) { const unsigned a = ror8_u(v.x), b = ror8_u(v.y), c = ror8_u(v.z), d = ror8_u(v.w); return (u32x4){a, b, c, d}; }
; __device__ __forceinline__ float fast_gelu_tanh(float x) { const float p = __builtin_fmaf(x * x, -0.10294324f, -2.3022082f);
;     return x * __builtin_amdgcn_rcpf(1.f + __builtin_amdgcn_exp2f(p * x)); }
;     __device__ __forceinline__ void epi(AccT& acc, const Unit& u, LAS unsigned char* lds, int wr, int wc, int fr, int fq) const {
; #pragma unroll
;         for (int ai = 0; ai < 2; ++ai)
; #pragma unroll
;             for (int m = 0; m < 4; ++m) { const bool lo = fr < 8; const int row = u.pm * 256 + ai * 128 + wr * 64 + m * 16 + (fr & 7); bf16_t* rp = ZT + (size_t)u.pn * T * 16 + (size_t)row * 256 + wc * 64 + (lo ? 0 : 32) + 8 * fq; u32x4 w[2];
; #pragma unroll
;                 for (int bj = 0; bj < 2; ++bj) { const f32x4 v0 = acc[ai][bj][m][0], v1 = acc[ai][bj][m][1];
;                     w[bj].x = cvt_pk_bf16(fast_gelu_tanh(v0[0]), fast_gelu_tanh(v0[1])); w[bj].y = cvt_pk_bf16(fast_gelu_tanh(v0[2]), fast_gelu_tanh(v0[3]));
;                     w[bj].z = cvt_pk_bf16(fast_gelu_tanh(v1[0]), fast_gelu_tanh(v1[1])); w[bj].w = cvt_pk_bf16(fast_gelu_tanh(v1[2]), fast_gelu_tanh(v1[3])); }
;                 const u32x4 r0 = ror8_u4(w[0]), r1 = ror8_u4(w[1]); store16_wt(rp, lo ? w[0] : r1); store16_wt(rp + 8 * 256, lo ? r0 : w[1]); }
;     }
	v_cvt_pk_bf16_f32 v183, v74, v75
	v_cvt_pk_bf16_f32 v184, v68, v69
	v_cvt_pk_bf16_f32 v185, v70, v71
	v_cvt_pk_bf16_f32 v186, v64, v65
	v_cvt_pk_bf16_f32 v187, v66, v67
	v_mov_b32_dpp v190, v184 row_ror:8 row_mask:0xf bank_mask:0xf bound_ctrl:1
	v_mov_b32_dpp v191, v185 row_ror:8 row_mask:0xf bank_mask:0xf bound_ctrl:1
	v_mov_b32_dpp v192, v186 row_ror:8 row_mask:0xf bank_mask:0xf bound_ctrl:1
	v_mov_b32_dpp v193, v187 row_ror:8 row_mask:0xf bank_mask:0xf bound_ctrl:1
	v_cndmask_b32_e32 v194, v190, v180, vcc
	v_cndmask_b32_e32 v195, v191, v181, vcc
	v_cndmask_b32_e32 v196, v192, v182, vcc
	v_cndmask_b32_e32 v197, v193, v183, vcc
	global_store_dwordx4 v[152:153], v[194:197], off sc1
	s_nop 1
	v_mov_b32_dpp v190, v180 row_ror:8 row_mask:0xf bank_mask:0xf bound_ctrl:1
	v_mov_b32_dpp v191, v181 row_ror:8 row_mask:0xf bank_mask:0xf bound_ctrl:1
	v_mov_b32_dpp v192, v182 row_ror:8 row_mask:0xf bank_mask:0xf bound_ctrl:1
	v_mov_b32_dpp v193, v183 row_ror:8 row_mask:0xf bank_mask:0xf bound_ctrl:1
	v_cndmask_b32_e32 v198, v184, v190, vcc
	v_cndmask_b32_e32 v199, v185, v191, vcc
	v_cndmask_b32_e32 v200, v186, v192, vcc
	v_cndmask_b32_e32 v201, v187, v193, vcc
	v_lshl_add_u64 v[152:153], v[152:153], 0, s[6:7]
	global_store_dwordx4 v[152:153], v[198:201], off sc1
	s_nop 1
	v_pk_mul_f32 v[160:161], v[60:61], v[60:61]
	v_pk_mul_f32 v[162:163], v[62:63], v[62:63]
	v_pk_mul_f32 v[164:165], v[56:57], v[56:57]
	v_pk_mul_f32 v[166:167], v[58:59], v[58:59]
	v_pk_mul_f32 v[168:169], v[52:53], v[52:53]
	v_pk_mul_f32 v[170:171], v[54:55], v[54:55]
	v_pk_mul_f32 v[172:173], v[48:49], v[48:49]
	v_pk_mul_f32 v[174:175], v[50:51], v[50:51]
	v_pk_fma_f32 v[160:161], v[160:161], v[140:141], v[142:143]
	v_pk_fma_f32 v[162:163], v[162:163], v[140:141], v[142:143]
	v_pk_fma_f32 v[164:165], v[164:165], v[140:141], v[142:143]
	v_pk_fma_f32 v[166:167], v[166:167], v[140:141], v[142:143]
	v_pk_fma_f32 v[168:169], v[168:169], v[140:141], v[142:143]
	v_pk_fma_f32 v[170:171], v[170:171], v[140:141], v[142:143]
	v_pk_fma_f32 v[172:173], v[172:173], v[140:141], v[142:143]
	v_pk_fma_f32 v[174:175], v[174:175], v[140:141], v[142:143]
	v_pk_mul_f32 v[160:161], v[60:61], v[160:161]
	v_pk_mul_f32 v[162:163], v[62:63], v[162:163]
	v_pk_mul_f32 v[164:165], v[56:57], v[164:165]
	v_pk_mul_f32 v[166:167], v[58:59], v[166:167]
	v_pk_mul_f32 v[168:169], v[52:53], v[168:169]
	v_pk_mul_f32 v[170:171], v[54:55], v[170:171]
	v_pk_mul_f32 v[172:173], v[48:49], v[172:173]
	v_pk_mul_f32 v[174:175], v[50:51], v[174:175]
	v_exp_f32_e32 v160, v160
	v_exp_f32_e32 v161, v161
	v_exp_f32_e32 v162, v162
	v_exp_f32_e32 v163, v163
	v_exp_f32_e32 v164, v164
	v_exp_f32_e32 v165, v165
	v_exp_f32_e32 v166, v166
	v_exp_f32_e32 v167, v167
	v_exp_f32_e32 v168, v168
	v_exp_f32_e32 v169, v169
	v_exp_f32_e32 v170, v170
	v_exp_f32_e32 v171, v171
	v_exp_f32_e32 v172, v172
	v_exp_f32_e32 v173, v173
	v_exp_f32_e32 v174, v174
	v_exp_f32_e32 v175, v175
	v_add_u32_e32 v152, 0x80, v146
	v_mov_b32_e32 v153, 0
	v_pk_add_f32 v[160:161], v[160:161], v[144:145]
	v_pk_add_f32 v[162:163], v[162:163], v[144:145]
	v_pk_add_f32 v[164:165], v[164:165], v[144:145]
	v_pk_add_f32 v[166:167], v[166:167], v[144:145]
	v_pk_add_f32 v[168:169], v[168:169], v[144:145]
	v_pk_add_f32 v[170:171], v[170:171], v[144:145]
	v_pk_add_f32 v[172:173], v[172:173], v[144:145]
	v_pk_add_f32 v[174:175], v[174:175], v[144:145]
	v_rcp_f32_e32 v160, v160
	v_rcp_f32_e32 v161, v161
	v_rcp_f32_e32 v162, v162
	v_rcp_f32_e32 v163, v163
	v_rcp_f32_e32 v164, v164
	v_rcp_f32_e32 v165, v165
	v_rcp_f32_e32 v166, v166
	v_rcp_f32_e32 v167, v167
	v_rcp_f32_e32 v168, v168
	v_rcp_f32_e32 v169, v169
	v_rcp_f32_e32 v170, v170
	v_rcp_f32_e32 v171, v171
	v_rcp_f32_e32 v172, v172
	v_rcp_f32_e32 v173, v173
	v_rcp_f32_e32 v174, v174
	v_rcp_f32_e32 v175, v175
	v_lshlrev_b64 v[152:153], 9, v[152:153]
	v_lshl_add_u64 v[152:153], v[148:149], 0, v[152:153]
	v_pk_mul_f32 v[60:61], v[60:61], v[160:161]
	v_pk_mul_f32 v[62:63], v[62:63], v[162:163]
	v_pk_mul_f32 v[56:57], v[56:57], v[164:165]
	v_pk_mul_f32 v[58:59], v[58:59], v[166:167]
	v_pk_mul_f32 v[52:53], v[52:53], v[168:169]
	v_pk_mul_f32 v[54:55], v[54:55], v[170:171]
	v_pk_mul_f32 v[48:49], v[48:49], v[172:173]
	v_pk_mul_f32 v[50:51], v[50:51], v[174:175]
	v_cvt_pk_bf16_f32 v180, v60, v61
	v_cvt_pk_bf16_f32 v181, v62, v63
	v_cvt_pk_bf16_f32 v182, v56, v57
	v_cvt_pk_bf16_f32 v183, v58, v59
	v_cvt_pk_bf16_f32 v184, v52, v53
	v_cvt_pk_bf16_f32 v185, v54, v55
	v_cvt_pk_bf16_f32 v186, v48, v49
	v_cvt_pk_bf16_f32 v187, v50, v51
	v_mov_b32_dpp v190, v184 row_ror:8 row_mask:0xf bank_mask:0xf bound_ctrl:1
	v_mov_b32_dpp v191, v185 row_ror:8 row_mask:0xf bank_mask:0xf bound_ctrl:1
	v_mov_b32_dpp v192, v186 row_ror:8 row_mask:0xf bank_mask:0xf bound_ctrl:1
	v_mov_b32_dpp v193, v187 row_ror:8 row_mask:0xf bank_mask:0xf bound_ctrl:1
	v_cndmask_b32_e32 v194, v190, v180, vcc
	v_cndmask_b32_e32 v195, v191, v181, vcc
	v_cndmask_b32_e32 v196, v192, v182, vcc
	v_cndmask_b32_e32 v197, v193, v183, vcc
	global_store_dwordx4 v[152:153], v[194:197], off sc1
	s_nop 1
	v_mov_b32_dpp v190, v180 row_ror:8 row_mask:0xf bank_mask:0xf bound_ctrl:1
	v_mov_b32_dpp v191, v181 row_ror:8 row_mask:0xf bank_mask:0xf bound_ctrl:1
	v_mov_b32_dpp v192, v182 row_ror:8 row_mask:0xf bank_mask:0xf bound_ctrl:1
	v_mov_b32_dpp v193, v183 row_ror:8 row_mask:0xf bank_mask:0xf bound_ctrl:1
	v_cndmask_b32_e32 v198, v184, v190, vcc
	v_cndmask_b32_e32 v199, v185, v191, vcc
	v_cndmask_b32_e32 v200, v186, v192, vcc
	v_cndmask_b32_e32 v201, v187, v193, vcc
	v_lshl_add_u64 v[152:153], v[152:153], 0, s[6:7]
	global_store_dwordx4 v[152:153], v[198:201], off sc1
	s_nop 1
; __device__ __forceinline__ unsigned cvt_pk_bf16(float lo, float hi) { const f32x2 v = {lo, hi}; const bf16x2_t b = __builtin_convertvector(v, bf16x2_t); return __builtin_bit_cast(unsigned, b); }
; __device__ __forceinline__ void store16_wt(void* p, u32x4 v) { asm volatile("global_store_dwordx4 %0, %1, off sc1\n\ts_nop 1" :: "v"(p), "v"(v) : "memory"); }
; __device__ __forceinline__ u32x4 ror8_u4(u32x4 v) { const unsigned a = ror8_u(v.x), b = ror8_u(v.y), c = ror8_u(v.z), d = ror8_u(v.w); return (u32x4){a, b, c, d}; }
; __device__ __forceinline__ float fast_gelu_tanh(float x) { const float p = __builtin_fmaf(x * x, -0.10294324f, -2.3022082f);
;     return x * __builtin_amdgcn_rcpf(1.f + __builtin_amdgcn_exp2f(p * x)); }
;     __device__ __forceinline__ void epi(AccT& acc, const Unit& u, LAS unsigned char* lds, int wr, int wc, int fr, int fq) const {
;     ...
;             for (int m = 0; m < 4; ++m) { const bool lo = fr < 8; const int row = u.pm * 256 + ai * 128 + wr * 64 + m * 16 + (fr & 7); bf16_t* rp = ZT + (size_t)u.pn * T * 16 + (size_t)row * 256 + wc * 64 + (lo ? 0 : 32) + 8 * fq; u32x4 w[2];
; #pragma unroll
;                 for (int bj = 0; bj < 2; ++bj) { const f32x4 v0 = acc[ai][bj][m][0], v1 = acc[ai][bj][m][1];
;                     w[bj].x = cvt_pk_bf16(fast_gelu_tanh(v0[0]), fast_gelu_tanh(v0[1])); w[bj].y = cvt_pk_bf16(fast_gelu_tanh(v0[2]), fast_gelu_tanh(v0[3]));
;                     w[bj].z = cvt_pk_bf16(fast_gelu_tanh(v1[0]), fast_gelu_tanh(v1[1])); w[bj].w = cvt_pk_bf16(fast_gelu_tanh(v1[2]), fast_gelu_tanh(v1[3])); }
;                 const u32x4 r0 = ror8_u4(w[0]), r1 = ror8_u4(w[1]); store16_wt(rp, lo ? w[0] : r1); store16_wt(rp + 8 * 256, lo ? r0 : w[1]); }
	v_pk_mul_f32 v[160:161], v[44:45], v[44:45]
	v_pk_mul_f32 v[162:163], v[46:47], v[46:47]
	v_pk_mul_f32 v[164:165], v[40:41], v[40:41]
	v_pk_mul_f32 v[166:167], v[42:43], v[42:43]
	v_pk_mul_f32 v[168:169], v[36:37], v[36:37]
	v_pk_mul_f32 v[170:171], v[38:39], v[38:39]
	v_pk_mul_f32 v[172:173], v[32:33], v[32:33]
	v_pk_mul_f32 v[174:175], v[34:35], v[34:35]
	v_pk_fma_f32 v[160:161], v[160:161], v[140:141], v[142:143]
	v_pk_fma_f32 v[162:163], v[162:163], v[140:141], v[142:143]
	v_pk_fma_f32 v[164:165], v[164:165], v[140:141], v[142:143]
	v_pk_fma_f32 v[166:167], v[166:167], v[140:141], v[142:143]
	v_pk_fma_f32 v[168:169], v[168:169], v[140:141], v[142:143]
	v_pk_fma_f32 v[170:171], v[170:171], v[140:141], v[142:143]
	v_pk_fma_f32 v[172:173], v[172:173], v[140:141], v[142:143]
	v_pk_fma_f32 v[174:175], v[174:175], v[140:141], v[142:143]
	v_pk_mul_f32 v[160:161], v[44:45], v[160:161]
	v_pk_mul_f32 v[162:163], v[46:47], v[162:163]
	v_pk_mul_f32 v[164:165], v[40:41], v[164:165]
	v_pk_mul_f32 v[166:167], v[42:43], v[166:167]
	v_pk_mul_f32 v[168:169], v[36:37], v[168:169]
	v_pk_mul_f32 v[170:171], v[38:39], v[170:171]
	v_pk_mul_f32 v[172:173], v[32:33], v[172:173]
	v_pk_mul_f32 v[174:175], v[34:35], v[174:175]
	v_exp_f32_e32 v160, v160
	v_exp_f32_e32 v161, v161
	v_exp_f32_e32 v162, v162
	v_exp_f32_e32 v163, v163
	v_exp_f32_e32 v164, v164
	v_exp_f32_e32 v165, v165
	v_exp_f32_e32 v166, v166
	v_exp_f32_e32 v167, v167
	v_exp_f32_e32 v168, v168
	v_exp_f32_e32 v169, v169
	v_exp_f32_e32 v170, v170
	v_exp_f32_e32 v171, v171
	v_exp_f32_e32 v172, v172
	v_exp_f32_e32 v173, v173
	v_exp_f32_e32 v174, v174
	v_exp_f32_e32 v175, v175
	v_add_u32_e32 v152, 0x90, v146
	v_mov_b32_e32 v153, 0
	v_pk_add_f32 v[160:161], v[160:161], v[144:145]
	v_pk_add_f32 v[162:163], v[162:163], v[144:145]
	v_pk_add_f32 v[164:165], v[164:165], v[144:145]
	v_pk_add_f32 v[166:167], v[166:167], v[144:145]
	v_pk_add_f32 v[168:169], v[168:169], v[144:145]
	v_pk_add_f32 v[170:171], v[170:171], v[144:145]
	v_pk_add_f32 v[172:173], v[172:173], v[144:145]
	v_pk_add_f32 v[174:175], v[174:175], v[144:145]
	v_rcp_f32_e32 v160, v160
	v_rcp_f32_e32 v161, v161
	v_rcp_f32_e32 v162, v162
	v_rcp_f32_e32 v163, v163
	v_rcp_f32_e32 v164, v164
	v_rcp_f32_e32 v165, v165
	v_rcp_f32_e32 v166, v166
	v_rcp_f32_e32 v167, v167
	v_rcp_f32_e32 v168, v168
	v_rcp_f32_e32 v169, v169
	v_rcp_f32_e32 v170, v170
	v_rcp_f32_e32 v171, v171
	v_rcp_f32_e32 v172, v172
	v_rcp_f32_e32 v173, v173
	v_rcp_f32_e32 v174, v174
	v_rcp_f32_e32 v175, v175
	v_lshlrev_b64 v[152:153], 9, v[152:153]
	v_lshl_add_u64 v[152:153], v[148:149], 0, v[152:153]
	v_pk_mul_f32 v[44:45], v[44:45], v[160:161]
	v_pk_mul_f32 v[46:47], v[46:47], v[162:163]
	v_pk_mul_f32 v[40:41], v[40:41], v[164:165]
	v_pk_mul_f32 v[42:43], v[42:43], v[166:167]
	v_pk_mul_f32 v[36:37], v[36:37], v[168:169]
	v_pk_mul_f32 v[38:39], v[38:39], v[170:171]
	v_pk_mul_f32 v[32:33], v[32:33], v[172:173]
	v_pk_mul_f32 v[34:35], v[34:35], v[174:175]
	v_cvt_pk_bf16_f32 v180, v44, v45
	v_cvt_pk_bf16_f32 v181, v46, v47
	v_cvt_pk_bf16_f32 v182, v40, v41
	v_cvt_pk_bf16_f32 v183, v42, v43
	v_cvt_pk_bf16_f32 v184, v36, v37
	v_cvt_pk_bf16_f32 v185, v38, v39
	v_cvt_pk_bf16_f32 v186, v32, v33
	v_cvt_pk_bf16_f32 v187, v34, v35
	v_mov_b32_dpp v190, v184 row_ror:8 row_mask:0xf bank_mask:0xf bound_ctrl:1
	v_mov_b32_dpp v191, v185 row_ror:8 row_mask:0xf bank_mask:0xf bound_ctrl:1
	v_mov_b32_dpp v192, v186 row_ror:8 row_mask:0xf bank_mask:0xf bound_ctrl:1
	v_mov_b32_dpp v193, v187 row_ror:8 row_mask:0xf bank_mask:0xf bound_ctrl:1
	v_cndmask_b32_e32 v194, v190, v180, vcc
	v_cndmask_b32_e32 v195, v191, v181, vcc
	v_cndmask_b32_e32 v196, v192, v182, vcc
	v_cndmask_b32_e32 v197, v193, v183, vcc
	global_store_dwordx4 v[152:153], v[194:197], off sc1
	s_nop 1
	v_mov_b32_dpp v190, v180 row_ror:8 row_mask:0xf bank_mask:0xf bound_ctrl:1
	v_mov_b32_dpp v191, v181 row_ror:8 row_mask:0xf bank_mask:0xf bound_ctrl:1
	v_mov_b32_dpp v192, v182 row_ror:8 row_mask:0xf bank_mask:0xf bound_ctrl:1
	v_mov_b32_dpp v193, v183 row_ror:8 row_mask:0xf bank_mask:0xf bound_ctrl:1
	v_cndmask_b32_e32 v198, v184, v190, vcc
	v_cndmask_b32_e32 v199, v185, v191, vcc
	v_cndmask_b32_e32 v200, v186, v192, vcc
	v_cndmask_b32_e32 v201, v187, v193, vcc
	v_lshl_add_u64 v[152:153], v[152:153], 0, s[6:7]
	global_store_dwordx4 v[152:153], v[198:201], off sc1
	s_nop 1
	v_pk_mul_f32 v[160:161], v[28:29], v[28:29]
	v_pk_mul_f32 v[162:163], v[30:31], v[30:31]
	v_pk_mul_f32 v[164:165], v[24:25], v[24:25]
	v_pk_mul_f32 v[166:167], v[26:27], v[26:27]
	v_pk_mul_f32 v[168:169], v[20:21], v[20:21]
	v_pk_mul_f32 v[170:171], v[22:23], v[22:23]
	v_pk_mul_f32 v[172:173], v[16:17], v[16:17]
	v_pk_mul_f32 v[174:175], v[18:19], v[18:19]
	v_pk_fma_f32 v[160:161], v[160:161], v[140:141], v[142:143]
	v_pk_fma_f32 v[162:163], v[162:163], v[140:141], v[142:143]
	v_pk_fma_f32 v[164:165], v[164:165], v[140:141], v[142:143]
	v_pk_fma_f32 v[166:167], v[166:167], v[140:141], v[142:143]
	v_pk_fma_f32 v[168:169], v[168:169], v[140:141], v[142:143]
	v_pk_fma_f32 v[170:171], v[170:171], v[140:141], v[142:143]
	v_pk_fma_f32 v[172:173], v[172:173], v[140:141], v[142:143]
	v_pk_fma_f32 v[174:175], v[174:175], v[140:141], v[142:143]
	v_pk_mul_f32 v[160:161], v[28:29], v[160:161]
	v_pk_mul_f32 v[162:163], v[30:31], v[162:163]
	v_pk_mul_f32 v[164:165], v[24:25], v[164:165]
	v_pk_mul_f32 v[166:167], v[26:27], v[166:167]
	v_pk_mul_f32 v[168:169], v[20:21], v[168:169]
	v_pk_mul_f32 v[170:171], v[22:23], v[170:171]
	v_pk_mul_f32 v[172:173], v[16:17], v[172:173]
	v_pk_mul_f32 v[174:175], v[18:19], v[174:175]
	v_exp_f32_e32 v160, v160
	v_exp_f32_e32 v161, v161
	v_exp_f32_e32 v162, v162
; __device__ __forceinline__ unsigned cvt_pk_bf16(float lo, float hi) { const f32x2 v = {lo, hi}; const bf16x2_t b = __builtin_convertvector(v, bf16x2_t); return __builtin_bit_cast(unsigned, b); }
; __device__ __forceinline__ void store16_wt(void* p, u32x4 v) { asm volatile("global_store_dwordx4 %0, %1, off sc1\n\ts_nop 1" :: "v"(p), "v"(v) : "memory"); }
; __device__ __forceinline__ u32x4 ror8_u4(u32x4 v) { const unsigned a = ror8_u(v.x), b = ror8_u(v.y), c = ror8_u(v.z), d = ror8_u(v.w); return (u32x4){a, b, c, d}; }
; __device__ __forceinline__ float fast_gelu_tanh(float x) { const float p = __builtin_fmaf(x * x, -0.10294324f, -2.3022082f);
;     return x * __builtin_amdgcn_rcpf(1.f + __builtin_amdgcn_exp2f(p * x)); }
;     __device__ __forceinline__ void epi(AccT& acc, const Unit& u, LAS unsigned char* lds, int wr, int wc, int fr, int fq) const {
;     ...
;             for (int m = 0; m < 4; ++m) { const bool lo = fr < 8; const int row = u.pm * 256 + ai * 128 + wr * 64 + m * 16 + (fr & 7); bf16_t* rp = ZT + (size_t)u.pn * T * 16 + (size_t)row * 256 + wc * 64 + (lo ? 0 : 32) + 8 * fq; u32x4 w[2];
; #pragma unroll
;                 for (int bj = 0; bj < 2; ++bj) { const f32x4 v0 = acc[ai][bj][m][0], v1 = acc[ai][bj][m][1];
;                     w[bj].x = cvt_pk_bf16(fast_gelu_tanh(v0[0]), fast_gelu_tanh(v0[1])); w[bj].y = cvt_pk_bf16(fast_gelu_tanh(v0[2]), fast_gelu_tanh(v0[3]));
;                     w[bj].z = cvt_pk_bf16(fast_gelu_tanh(v1[0]), fast_gelu_tanh(v1[1])); w[bj].w = cvt_pk_bf16(fast_gelu_tanh(v1[2]), fast_gelu_tanh(v1[3])); }
;                 const u32x4 r0 = ror8_u4(w[0]), r1 = ror8_u4(w[1]); store16_wt(rp, lo ? w[0] : r1); store16_wt(rp + 8 * 256, lo ? r0 : w[1]); }
	v_exp_f32_e32 v163, v163
	v_exp_f32_e32 v164, v164
	v_exp_f32_e32 v165, v165
	v_exp_f32_e32 v166, v166
	v_exp_f32_e32 v167, v167
	v_exp_f32_e32 v168, v168
	v_exp_f32_e32 v169, v169
	v_exp_f32_e32 v170, v170
	v_exp_f32_e32 v171, v171
	v_exp_f32_e32 v172, v172
	v_exp_f32_e32 v173, v173
	v_exp_f32_e32 v174, v174
	v_exp_f32_e32 v175, v175
	v_add_u32_e32 v152, 0xa0, v146
	v_mov_b32_e32 v153, 0
	v_pk_add_f32 v[160:161], v[160:161], v[144:145]
	v_pk_add_f32 v[162:163], v[162:163], v[144:145]
	v_pk_add_f32 v[164:165], v[164:165], v[144:145]
	v_pk_add_f32 v[166:167], v[166:167], v[144:145]
	v_pk_add_f32 v[168:169], v[168:169], v[144:145]
	v_pk_add_f32 v[170:171], v[170:171], v[144:145]
	v_pk_add_f32 v[172:173], v[172:173], v[144:145]
	v_pk_add_f32 v[174:175], v[174:175], v[144:145]
	v_rcp_f32_e32 v160, v160
	v_rcp_f32_e32 v161, v161
	v_rcp_f32_e32 v162, v162
	v_rcp_f32_e32 v163, v163
	v_rcp_f32_e32 v164, v164
	v_rcp_f32_e32 v165, v165
	v_rcp_f32_e32 v166, v166
	v_rcp_f32_e32 v167, v167
	v_rcp_f32_e32 v168, v168
	v_rcp_f32_e32 v169, v169
	v_rcp_f32_e32 v170, v170
	v_rcp_f32_e32 v171, v171
	v_rcp_f32_e32 v172, v172
	v_rcp_f32_e32 v173, v173
	v_rcp_f32_e32 v174, v174
	v_rcp_f32_e32 v175, v175
	v_lshlrev_b64 v[152:153], 9, v[152:153]
	v_lshl_add_u64 v[152:153], v[148:149], 0, v[152:153]
	v_pk_mul_f32 v[28:29], v[28:29], v[160:161]
	v_pk_mul_f32 v[30:31], v[30:31], v[162:163]
	v_pk_mul_f32 v[24:25], v[24:25], v[164:165]
	v_pk_mul_f32 v[26:27], v[26:27], v[166:167]
	v_pk_mul_f32 v[20:21], v[20:21], v[168:169]
	v_pk_mul_f32 v[22:23], v[22:23], v[170:171]
	v_pk_mul_f32 v[16:17], v[16:17], v[172:173]
	v_pk_mul_f32 v[18:19], v[18:19], v[174:175]
	v_cvt_pk_bf16_f32 v180, v28, v29
	v_cvt_pk_bf16_f32 v181, v30, v31
	v_cvt_pk_bf16_f32 v182, v24, v25
	v_cvt_pk_bf16_f32 v183, v26, v27
	v_cvt_pk_bf16_f32 v184, v20, v21
	v_cvt_pk_bf16_f32 v185, v22, v23
	v_cvt_pk_bf16_f32 v186, v16, v17
	v_cvt_pk_bf16_f32 v187, v18, v19
	v_mov_b32_dpp v190, v184 row_ror:8 row_mask:0xf bank_mask:0xf bound_ctrl:1
	v_mov_b32_dpp v191, v185 row_ror:8 row_mask:0xf bank_mask:0xf bound_ctrl:1
	v_mov_b32_dpp v192, v186 row_ror:8 row_mask:0xf bank_mask:0xf bound_ctrl:1
	v_mov_b32_dpp v193, v187 row_ror:8 row_mask:0xf bank_mask:0xf bound_ctrl:1
	v_cndmask_b32_e32 v194, v190, v180, vcc
	v_cndmask_b32_e32 v195, v191, v181, vcc
	v_cndmask_b32_e32 v196, v192, v182, vcc
	v_cndmask_b32_e32 v197, v193, v183, vcc
	global_store_dwordx4 v[152:153], v[194:197], off sc1
	s_nop 1
	v_mov_b32_dpp v190, v180 row_ror:8 row_mask:0xf bank_mask:0xf bound_ctrl:1
	v_mov_b32_dpp v191, v181 row_ror:8 row_mask:0xf bank_mask:0xf bound_ctrl:1
	v_mov_b32_dpp v192, v182 row_ror:8 row_mask:0xf bank_mask:0xf bound_ctrl:1
	v_mov_b32_dpp v193, v183 row_ror:8 row_mask:0xf bank_mask:0xf bound_ctrl:1
	v_cndmask_b32_e32 v198, v184, v190, vcc
	v_cndmask_b32_e32 v199, v185, v191, vcc
	v_cndmask_b32_e32 v200, v186, v192, vcc
	v_cndmask_b32_e32 v201, v187, v193, vcc
	v_lshl_add_u64 v[152:153], v[152:153], 0, s[6:7]
	global_store_dwordx4 v[152:153], v[198:201], off sc1
	s_nop 1
	v_pk_mul_f32 v[160:161], v[12:13], v[12:13]
	v_pk_mul_f32 v[162:163], v[14:15], v[14:15]
	v_pk_mul_f32 v[164:165], v[8:9], v[8:9]
	v_pk_mul_f32 v[166:167], v[10:11], v[10:11]
	v_pk_mul_f32 v[168:169], v[4:5], v[4:5]
	v_pk_mul_f32 v[170:171], v[6:7], v[6:7]
	v_pk_mul_f32 v[172:173], v[0:1], v[0:1]
	v_pk_mul_f32 v[174:175], v[2:3], v[2:3]
	v_pk_fma_f32 v[160:161], v[160:161], v[140:141], v[142:143]
	v_pk_fma_f32 v[162:163], v[162:163], v[140:141], v[142:143]
	v_pk_fma_f32 v[164:165], v[164:165], v[140:141], v[142:143]
	v_pk_fma_f32 v[166:167], v[166:167], v[140:141], v[142:143]
	v_pk_fma_f32 v[168:169], v[168:169], v[140:141], v[142:143]
; __device__ __forceinline__ unsigned cvt_pk_bf16(float lo, float hi) { const f32x2 v = {lo, hi}; const bf16x2_t b = __builtin_convertvector(v, bf16x2_t); return __builtin_bit_cast(unsigned, b); }
; __device__ __forceinline__ void store16_wt(void* p, u32x4 v) { asm volatile("global_store_dwordx4 %0, %1, off sc1\n\ts_nop 1" :: "v"(p), "v"(v) : "memory"); }
; __device__ __forceinline__ u32x4 ror8_u4(u32x4 v) { const unsigned a = ror8_u(v.x), b = ror8_u(v.y), c = ror8_u(v.z), d = ror8_u(v.w); return (u32x4){a, b, c, d}; }
; #define PG8_WAIT_V(n) asm volatile("s_waitcnt vmcnt(" #n ")" ::: "memory")
; #define PG8_BAR __builtin_amdgcn_s_barrier()
; template <class Prob, bool ALIGN_EPI, bool SP2>
; __device__ __forceinline__ void gemm_phase(LAS unsigned char* lds, const Prob& Pb, int wave, const char* wsb) {
;     ...
;     PG8_WAIT_V(0);
;     if constexpr (!ALIGN_EPI) { if (wr == 0) PG8_BAR; }
;     PG8_BAR;
;     __device__ __forceinline__ void epi(AccT& acc, const Unit& u, LAS unsigned char* lds, int wr, int wc, int fr, int fq) const {
;     ...
;             for (int m = 0; m < 4; ++m) { const bool lo = fr < 8; const int row = u.pm * 256 + ai * 128 + wr * 64 + m * 16 + (fr & 7); bf16_t* rp = ZT + (size_t)u.pn * T * 16 + (size_t)row * 256 + wc * 64 + (lo ? 0 : 32) + 8 * fq; u32x4 w[2];
; #pragma unroll
;                 for (int bj = 0; bj < 2; ++bj) { const f32x4 v0 = acc[ai][bj][m][0], v1 = acc[ai][bj][m][1];
;                     w[bj].x = cvt_pk_bf16(fast_gelu_tanh(v0[0]), fast_gelu_tanh(v0[1])); w[bj].y = cvt_pk_bf16(fast_gelu_tanh(v0[2]), fast_gelu_tanh(v0[3]));
;                     w[bj].z = cvt_pk_bf16(fast_gelu_tanh(v1[0]), fast_gelu_tanh(v1[1])); w[bj].w = cvt_pk_bf16(fast_gelu_tanh(v1[2]), fast_gelu_tanh(v1[3])); }
;                 const u32x4 r0 = ror8_u4(w[0]), r1 = ror8_u4(w[1]); store16_wt(rp, lo ? w[0] : r1); store16_wt(rp + 8 * 256, lo ? r0 : w[1]); }
	v_pk_fma_f32 v[170:171], v[170:171], v[140:141], v[142:143]
	v_pk_fma_f32 v[172:173], v[172:173], v[140:141], v[142:143]
	v_pk_fma_f32 v[174:175], v[174:175], v[140:141], v[142:143]
	v_pk_mul_f32 v[160:161], v[12:13], v[160:161]
	v_pk_mul_f32 v[162:163], v[14:15], v[162:163]
	v_pk_mul_f32 v[164:165], v[8:9], v[164:165]
	v_pk_mul_f32 v[166:167], v[10:11], v[166:167]
	v_pk_mul_f32 v[168:169], v[4:5], v[168:169]
	v_pk_mul_f32 v[170:171], v[6:7], v[170:171]
	v_pk_mul_f32 v[172:173], v[0:1], v[172:173]
	v_pk_mul_f32 v[174:175], v[2:3], v[174:175]
	v_exp_f32_e32 v160, v160
	v_exp_f32_e32 v161, v161
	v_exp_f32_e32 v162, v162
	v_exp_f32_e32 v163, v163
	v_exp_f32_e32 v164, v164
	v_exp_f32_e32 v165, v165
	v_exp_f32_e32 v166, v166
	v_exp_f32_e32 v167, v167
	v_exp_f32_e32 v168, v168
	v_exp_f32_e32 v169, v169
	v_exp_f32_e32 v170, v170
	v_exp_f32_e32 v171, v171
	v_exp_f32_e32 v172, v172
	v_exp_f32_e32 v173, v173
	v_exp_f32_e32 v174, v174
	v_exp_f32_e32 v175, v175
	v_add_u32_e32 v152, 0xb0, v146
	v_mov_b32_e32 v153, 0
	v_pk_add_f32 v[160:161], v[160:161], v[144:145]
	v_pk_add_f32 v[162:163], v[162:163], v[144:145]
	v_pk_add_f32 v[164:165], v[164:165], v[144:145]
	v_pk_add_f32 v[166:167], v[166:167], v[144:145]
	v_pk_add_f32 v[168:169], v[168:169], v[144:145]
	v_pk_add_f32 v[170:171], v[170:171], v[144:145]
	v_pk_add_f32 v[172:173], v[172:173], v[144:145]
	v_pk_add_f32 v[174:175], v[174:175], v[144:145]
	v_rcp_f32_e32 v160, v160
	v_rcp_f32_e32 v161, v161
	v_rcp_f32_e32 v162, v162
	v_rcp_f32_e32 v163, v163
	v_rcp_f32_e32 v164, v164
	v_rcp_f32_e32 v165, v165
	v_rcp_f32_e32 v166, v166
	v_rcp_f32_e32 v167, v167
	v_rcp_f32_e32 v168, v168
	v_rcp_f32_e32 v169, v169
	v_rcp_f32_e32 v170, v170
	v_rcp_f32_e32 v171, v171
	v_rcp_f32_e32 v172, v172
	v_rcp_f32_e32 v173, v173
	v_rcp_f32_e32 v174, v174
	v_rcp_f32_e32 v175, v175
	v_lshlrev_b64 v[152:153], 9, v[152:153]
	v_lshl_add_u64 v[152:153], v[148:149], 0, v[152:153]
	v_pk_mul_f32 v[12:13], v[12:13], v[160:161]
	v_pk_mul_f32 v[14:15], v[14:15], v[162:163]
	v_pk_mul_f32 v[8:9], v[8:9], v[164:165]
	v_pk_mul_f32 v[10:11], v[10:11], v[166:167]
	v_pk_mul_f32 v[4:5], v[4:5], v[168:169]
	v_pk_mul_f32 v[6:7], v[6:7], v[170:171]
	v_pk_mul_f32 v[0:1], v[0:1], v[172:173]
	v_pk_mul_f32 v[2:3], v[2:3], v[174:175]
	v_cvt_pk_bf16_f32 v180, v12, v13
	v_cvt_pk_bf16_f32 v181, v14, v15
	v_cvt_pk_bf16_f32 v182, v8, v9
	v_cvt_pk_bf16_f32 v183, v10, v11
	v_cvt_pk_bf16_f32 v184, v4, v5
	v_cvt_pk_bf16_f32 v185, v6, v7
	v_cvt_pk_bf16_f32 v186, v0, v1
	v_cvt_pk_bf16_f32 v187, v2, v3
	v_mov_b32_dpp v190, v184 row_ror:8 row_mask:0xf bank_mask:0xf bound_ctrl:1
	v_mov_b32_dpp v191, v185 row_ror:8 row_mask:0xf bank_mask:0xf bound_ctrl:1
	v_mov_b32_dpp v192, v186 row_ror:8 row_mask:0xf bank_mask:0xf bound_ctrl:1
	v_mov_b32_dpp v193, v187 row_ror:8 row_mask:0xf bank_mask:0xf bound_ctrl:1
	v_cndmask_b32_e32 v194, v190, v180, vcc
	v_cndmask_b32_e32 v195, v191, v181, vcc
	v_cndmask_b32_e32 v196, v192, v182, vcc
	v_cndmask_b32_e32 v197, v193, v183, vcc
	global_store_dwordx4 v[152:153], v[194:197], off sc1
	s_nop 1
	v_mov_b32_dpp v190, v180 row_ror:8 row_mask:0xf bank_mask:0xf bound_ctrl:1
	v_mov_b32_dpp v191, v181 row_ror:8 row_mask:0xf bank_mask:0xf bound_ctrl:1
	v_mov_b32_dpp v192, v182 row_ror:8 row_mask:0xf bank_mask:0xf bound_ctrl:1
	v_mov_b32_dpp v193, v183 row_ror:8 row_mask:0xf bank_mask:0xf bound_ctrl:1
	v_cndmask_b32_e32 v198, v184, v190, vcc
	v_cndmask_b32_e32 v199, v185, v191, vcc
	v_cndmask_b32_e32 v200, v186, v192, vcc
	v_cndmask_b32_e32 v201, v187, v193, vcc
	v_lshl_add_u64 v[152:153], v[152:153], 0, s[6:7]
	global_store_dwordx4 v[152:153], v[198:201], off sc1
	s_nop 1
	s_waitcnt vmcnt(0)
	s_barrier
